# P0 filter layer 4: all 32 w4 loads of a channel tile issued up front (was four dependent load->wait->MFMA groups)
# baseline (speedup 1.0000x reference)
; DI bf16 f2bf(float f) { return (bf16)(pk2(f, 0.f) & 0xffffu); }
; DI int crow(int reg, int h) { return (reg & 3) + 8 * (reg >> 2) + 4 * h; }
; DI void filter_unit(const Frame& F, int L, int p0, bf16* FR, float* F0, const float* w4, int ct0, int nct) {
;     ...
; #pragma unroll
;         for (int pt = 0; pt < 2; ++pt) {
;             const int ps = p0 + 32 * pt + r32; const float tpos = (float)ps / (float)(L - 1);
; #pragma unroll
;             for (int i = 0; i < 16; ++i) {
;                 const int c = (32 * ct + crow(i, hh)) & 511;
;                 const float delta = fabsf(mind + (float)c * ((maxd - mind) / 511.0f));
;                 const float val = (pt == 0 ? acc0[i] : acc1[i]) * __expf(-tpos * delta);
;                 bf16* row = FR + (size_t)c * 2 * L;
;                 if (ps == 0) { F0[dir * 512 + c] = val; if (dir == 0) row[0] = 0; }
;                 else row[dir ? L + ps : L - ps] = f2bf(val);
;             }
;         }
;     }
.LBB0_190:
	s_or_b64 exec, exec, s[18:19]
	v_mul_f32_e64 v68, v107, |v109|
	v_mul_f32_e32 v68, 0x3fb8aa3b, v68
	v_exp_f32_e32 v68, v68
	v_cndmask_b32_e64 v74, v104, v108, s[6:7]
	v_add_u32_e32 v74, 0x4000, v74
	v_ashrrev_i32_e32 v75, 31, v74
	v_mul_f32_e32 v0, v68, v0
	v_mul_f32_e64 v68, v107, |v110|
	v_mul_f32_e32 v68, 0x3fb8aa3b, v68
	v_exp_f32_e32 v68, v68
	v_lshlrev_b64 v[74:75], 1, v[74:75]
	v_cvt_pk_bf16_f32 v0, v0, s0
	v_lshl_add_u64 v[72:73], v[72:73], 0, v[74:75]
	global_store_short v[72:73], v0, off
	v_mul_f32_e32 v0, v68, v1
	v_mul_f32_e64 v1, v107, |v112|
	v_mul_f32_e32 v1, 0x3fb8aa3b, v1
	v_exp_f32_e32 v68, v1
	v_cvt_pk_bf16_f32 v72, v0, s0
	v_lshl_add_u64 v[0:1], v[16:17], 0, v[74:75]
	global_store_short v[0:1], v72, off
	v_mul_f32_e64 v1, v107, |v113|
	v_mul_f32_e32 v1, 0x3fb8aa3b, v1
	v_mul_f32_e32 v0, v68, v2
	v_exp_f32_e32 v2, v1
	v_cvt_pk_bf16_f32 v16, v0, s0
	v_lshl_add_u64 v[0:1], v[76:77], 0, v[74:75]
	global_store_short v[0:1], v16, off
	v_mul_f32_e64 v1, v107, |v114|
	v_mul_f32_e32 v1, 0x3fb8aa3b, v1
	v_mul_f32_e32 v0, v2, v3
	v_exp_f32_e32 v2, v1
	v_cvt_pk_bf16_f32 v3, v0, s0
	v_lshl_add_u64 v[0:1], v[18:19], 0, v[74:75]
	global_store_short v[0:1], v3, off
	v_mul_f32_e64 v1, v107, |v115|
	v_mul_f32_e32 v1, 0x3fb8aa3b, v1
	v_mul_f32_e32 v0, v2, v4
	v_exp_f32_e32 v2, v1
	v_cvt_pk_bf16_f32 v3, v0, s0
	v_lshl_add_u64 v[0:1], v[78:79], 0, v[74:75]
	global_store_short v[0:1], v3, off
	v_mul_f32_e64 v1, v107, |v116|
	v_mul_f32_e32 v1, 0x3fb8aa3b, v1
	v_mul_f32_e32 v0, v2, v5
	v_exp_f32_e32 v2, v1
	v_cvt_pk_bf16_f32 v3, v0, s0
	v_lshl_add_u64 v[0:1], v[20:21], 0, v[74:75]
	global_store_short v[0:1], v3, off
	v_mul_f32_e64 v1, v107, |v117|
	v_mul_f32_e32 v1, 0x3fb8aa3b, v1
	v_mul_f32_e32 v0, v2, v6
	v_exp_f32_e32 v2, v1
	v_cvt_pk_bf16_f32 v3, v0, s0
	v_lshl_add_u64 v[0:1], v[80:81], 0, v[74:75]
	global_store_short v[0:1], v3, off
	v_mul_f32_e64 v1, v107, |v118|
	v_mul_f32_e32 v1, 0x3fb8aa3b, v1
	v_mul_f32_e32 v0, v2, v7
	v_exp_f32_e32 v2, v1
	v_cvt_pk_bf16_f32 v3, v0, s0
	v_lshl_add_u64 v[0:1], v[22:23], 0, v[74:75]
	global_store_short v[0:1], v3, off
	v_mul_f32_e64 v1, v107, |v119|
	v_mul_f32_e32 v1, 0x3fb8aa3b, v1
	v_mul_f32_e32 v0, v2, v8
	v_exp_f32_e32 v2, v1
	v_cvt_pk_bf16_f32 v3, v0, s0
	v_lshl_add_u64 v[0:1], v[82:83], 0, v[74:75]
	global_store_short v[0:1], v3, off
	v_mul_f32_e64 v1, v107, |v120|
	v_mul_f32_e32 v1, 0x3fb8aa3b, v1
	v_mul_f32_e32 v0, v2, v9
	v_exp_f32_e32 v2, v1
	v_cvt_pk_bf16_f32 v3, v0, s0
	v_lshl_add_u64 v[0:1], v[24:25], 0, v[74:75]
	global_store_short v[0:1], v3, off
	v_mul_f32_e64 v1, v107, |v121|
	v_mul_f32_e32 v1, 0x3fb8aa3b, v1
	v_mul_f32_e32 v0, v2, v10
	v_exp_f32_e32 v2, v1
	v_cvt_pk_bf16_f32 v3, v0, s0
	v_lshl_add_u64 v[0:1], v[84:85], 0, v[74:75]
	global_store_short v[0:1], v3, off
	v_mul_f32_e64 v1, v107, |v122|
	v_mul_f32_e32 v1, 0x3fb8aa3b, v1
	v_mul_f32_e32 v0, v2, v11
	v_exp_f32_e32 v2, v1
	v_cvt_pk_bf16_f32 v3, v0, s0
	v_lshl_add_u64 v[0:1], v[26:27], 0, v[74:75]
	global_store_short v[0:1], v3, off
	v_mul_f32_e64 v1, v107, |v123|
	v_mul_f32_e32 v1, 0x3fb8aa3b, v1
	v_mul_f32_e32 v0, v2, v12
	v_exp_f32_e32 v2, v1
	v_cvt_pk_bf16_f32 v3, v0, s0
	v_lshl_add_u64 v[0:1], v[86:87], 0, v[74:75]
	global_store_short v[0:1], v3, off
	v_mul_f32_e64 v1, v107, |v124|
	v_mul_f32_e32 v1, 0x3fb8aa3b, v1
	v_mul_f32_e32 v0, v2, v13
	v_exp_f32_e32 v2, v1
	v_cvt_pk_bf16_f32 v3, v0, s0
	v_lshl_add_u64 v[0:1], v[28:29], 0, v[74:75]
	global_store_short v[0:1], v3, off
	v_mul_f32_e64 v1, v107, |v111|
	v_mul_f32_e32 v1, 0x3fb8aa3b, v1
	v_mul_f32_e32 v0, v2, v14
	v_exp_f32_e32 v2, v1
	v_cvt_pk_bf16_f32 v3, v0, s0
	v_lshl_add_u64 v[0:1], v[88:89], 0, v[74:75]
	s_add_u32 s16, s16, 0x80
	global_store_short v[0:1], v3, off
	v_mul_f32_e32 v0, v2, v15
	s_addc_u32 s17, s17, 0
	s_add_i32 s45, s45, 1
	s_add_i32 s44, s44, 32
	v_cvt_pk_bf16_f32 v2, v0, s0
	v_lshl_add_u64 v[0:1], v[30:31], 0, v[74:75]
	s_cmpk_lg_i32 s16, 0x200
	global_store_short v[0:1], v2, off
	s_cbranch_scc0 .LBB0_180
	s_nop 0
	s_nop 0
; DI unsigned pk2(float lo, float hi) { f32x2_t v = {lo, hi}; bf16x2_t b = __builtin_convertvector(v, bf16x2_t); return __builtin_bit_cast(unsigned, b); }
; DI int crow(int reg, int h) { return (reg & 3) + 8 * (reg >> 2) + 4 * h; }
; DI void filter_unit(const Frame& F, int L, int p0, bf16* FR, float* F0, const float* w4, int ct0, int nct) {
;     ...
;         for (int s = 0; s < 4; ++s) {
;             const float* wp = w4 + (size_t)(16 * s + 8 * hh) * 1024 + 32 * ct + r32;
;             u32x4 aw; aw.x = pk2(wp[0], wp[1024]); aw.y = pk2(wp[2048], wp[3072]); aw.z = pk2(wp[4096], wp[5120]); aw.w = pk2(wp[6144], wp[7168]);
;             const bf16x8 af = __builtin_bit_cast(bf16x8, aw);
;             acc0 = __builtin_amdgcn_mfma_f32_32x32x16_bf16(af, bfr[0][s], acc0, 0, 0, 0);
;             acc1 = __builtin_amdgcn_mfma_f32_32x32x16_bf16(af, bfr[1][s], acc1, 0, 0, 0);
;         }
; #pragma unroll
;         for (int pt = 0; pt < 2; ++pt) {
;             const int ps = p0 + 32 * pt + r32; const float tpos = (float)ps / (float)(L - 1);
; #pragma unroll
;             for (int i = 0; i < 16; ++i) {
;                 const int c = (32 * ct + crow(i, hh)) & 511;
;                 const float delta = fabsf(mind + (float)c * ((maxd - mind) / 511.0f));
;                 const float val = (pt == 0 ? acc0[i] : acc1[i]) * __expf(-tpos * delta);
.LBB0_191:
	v_lshl_add_u64 v[72:73], v[70:71], 0, s[16:17]
	s_cmp_lt_u32 s45, 16
	s_cselect_b64 s[6:7], -1, 0
	s_mov_b32 s99, 0
	s_mov_b32 s98, 0x1000
	v_lshl_add_u64 v[152:153], v[72:73], 0, s[98:99]
	s_mov_b32 s98, 0x3000
	v_lshl_add_u64 v[154:155], v[72:73], 0, s[98:99]
	s_mov_b32 s98, 0x5000
	v_lshl_add_u64 v[156:157], v[72:73], 0, s[98:99]
	s_mov_b32 s98, 0x7000
	v_lshl_add_u64 v[158:159], v[72:73], 0, s[98:99]
	s_mov_b32 s98, 0x11000
	v_lshl_add_u64 v[160:161], v[72:73], 0, s[98:99]
	s_mov_b32 s98, 0x13000
	v_lshl_add_u64 v[162:163], v[72:73], 0, s[98:99]
	s_mov_b32 s98, 0x15000
	v_lshl_add_u64 v[164:165], v[72:73], 0, s[98:99]
	s_mov_b32 s98, 0x17000
	v_lshl_add_u64 v[166:167], v[72:73], 0, s[98:99]
	s_mov_b32 s98, 0x21000
	v_lshl_add_u64 v[168:169], v[72:73], 0, s[98:99]
	s_mov_b32 s98, 0x23000
	v_lshl_add_u64 v[170:171], v[72:73], 0, s[98:99]
	s_mov_b32 s98, 0x25000
	v_lshl_add_u64 v[172:173], v[72:73], 0, s[98:99]
	s_mov_b32 s98, 0x27000
	v_lshl_add_u64 v[174:175], v[72:73], 0, s[98:99]
	s_mov_b32 s98, 0x31000
	v_lshl_add_u64 v[176:177], v[72:73], 0, s[98:99]
	s_mov_b32 s98, 0x33000
	v_lshl_add_u64 v[178:179], v[72:73], 0, s[98:99]
	s_mov_b32 s98, 0x35000
	v_lshl_add_u64 v[180:181], v[72:73], 0, s[98:99]
	s_mov_b32 s98, 0x37000
	v_lshl_add_u64 v[182:183], v[72:73], 0, s[98:99]
	global_load_dword v184, v[152:153], off offset:-4096
	global_load_dword v185, v[152:153], off
	global_load_dword v186, v[154:155], off offset:-4096
	global_load_dword v187, v[154:155], off
	global_load_dword v188, v[156:157], off offset:-4096
	global_load_dword v189, v[156:157], off
	global_load_dword v190, v[158:159], off offset:-4096
	global_load_dword v191, v[158:159], off
	global_load_dword v192, v[160:161], off offset:-4096
	global_load_dword v193, v[160:161], off
	global_load_dword v194, v[162:163], off offset:-4096
	global_load_dword v195, v[162:163], off
	global_load_dword v196, v[164:165], off offset:-4096
	global_load_dword v197, v[164:165], off
	global_load_dword v198, v[166:167], off offset:-4096
	global_load_dword v199, v[166:167], off
	global_load_dword v200, v[168:169], off offset:-4096
	global_load_dword v201, v[168:169], off
	global_load_dword v202, v[170:171], off offset:-4096
	global_load_dword v203, v[170:171], off
	global_load_dword v204, v[172:173], off offset:-4096
	global_load_dword v205, v[172:173], off
	global_load_dword v206, v[174:175], off offset:-4096
	global_load_dword v207, v[174:175], off
	global_load_dword v208, v[176:177], off offset:-4096
	global_load_dword v209, v[176:177], off
	global_load_dword v210, v[178:179], off offset:-4096
	global_load_dword v211, v[178:179], off
	global_load_dword v212, v[180:181], off offset:-4096
	global_load_dword v213, v[180:181], off
	global_load_dword v214, v[182:183], off offset:-4096
	global_load_dword v215, v[182:183], off
	s_waitcnt lgkmcnt(0)
	s_waitcnt vmcnt(24)
	v_cvt_pk_bf16_f32 v216, v184, v185
	v_cvt_pk_bf16_f32 v217, v186, v187
	v_cvt_pk_bf16_f32 v218, v188, v189
	v_cvt_pk_bf16_f32 v219, v190, v191
	s_nop 1
	v_mfma_f32_32x32x16_bf16 v[16:31], v[216:219], v[32:35], 0
	v_mfma_f32_32x32x16_bf16 v[0:15], v[216:219], v[48:51], 0
	s_waitcnt vmcnt(16)
	v_cvt_pk_bf16_f32 v220, v192, v193
	v_cvt_pk_bf16_f32 v221, v194, v195
	v_cvt_pk_bf16_f32 v222, v196, v197
	v_cvt_pk_bf16_f32 v223, v198, v199
	s_nop 1
	v_mfma_f32_32x32x16_bf16 v[16:31], v[220:223], v[36:39], v[16:31]
	v_mfma_f32_32x32x16_bf16 v[0:15], v[220:223], v[52:55], v[0:15]
	s_waitcnt vmcnt(8)
	v_cvt_pk_bf16_f32 v224, v200, v201
	v_cvt_pk_bf16_f32 v225, v202, v203
	v_cvt_pk_bf16_f32 v226, v204, v205
	v_cvt_pk_bf16_f32 v227, v206, v207
	s_nop 1
	v_mfma_f32_32x32x16_bf16 v[16:31], v[224:227], v[40:43], v[16:31]
	v_mfma_f32_32x32x16_bf16 v[0:15], v[224:227], v[56:59], v[0:15]
	s_waitcnt vmcnt(0)
	v_cvt_pk_bf16_f32 v228, v208, v209
	v_cvt_pk_bf16_f32 v229, v210, v211
	v_cvt_pk_bf16_f32 v230, v212, v213
	v_cvt_pk_bf16_f32 v231, v214, v215
	v_add_u32_e32 v76, s44, v94
	v_and_b32_e32 v111, 0x1e4, v76
	v_cvt_f32_u32_e32 v68, v111
	v_fmamk_f32 v109, v68, 0xbcc4df2d, v102
	v_mul_f32_e64 v68, v105, |v109|
	v_mul_f32_e32 v68, 0x3fb8aa3b, v68
	v_exp_f32_e32 v68, v68
	v_mfma_f32_32x32x16_bf16 v[16:31], v[228:231], v[44:47], v[16:31]
	v_mfma_f32_32x32x16_bf16 v[0:15], v[228:231], v[60:63], v[0:15]
	s_nop 1
	v_cndmask_b32_e64 v72, v103, v106, s[6:7]
	v_add_u32_e32 v74, 0x4000, v72
	s_nop 6
	v_mul_f32_e32 v16, v68, v16
	v_lshlrev_b32_e32 v68, 16, v111
	v_ashrrev_i32_e32 v75, 31, v74
	v_lshl_add_u64 v[72:73], s[40:41], 0, v[68:69]
	s_and_saveexec_b64 s[8:9], s[4:5]
	s_xor_b64 s[8:9], exec, s[8:9]
	s_cbranch_execz .LBB0_193
	v_cvt_pk_bf16_f32 v16, v16, s0
	v_lshl_add_u64 v[76:77], v[74:75], 1, v[72:73]
	global_store_short v[76:77], v16, off
